# P2 work rebalancing: compression-bias partial sum moved from workgroups 0-7 (which also own kmean items) to the last 8 workgroups; on top of v55
# speedup vs baseline: 1.0090x; 1.0006x over previous
.LBB0_695:
	s_cmp_lt_i32 s82, 3
	s_cselect_b64 s[0:1], -1, 0
	s_and_b64 s[0:1], s[0:1], s[6:7]
	s_andn2_b64 vcc, exec, s[0:1]
	s_cbranch_vccnz .LBB0_734
	s_load_dword s99, s[90:91], 0x110
	s_waitcnt lgkmcnt(0)
	s_sub_i32 s98, s94, s99
	s_add_i32 s98, s98, 8
	s_cmp_lt_u32 s98, 8
	s_cselect_b64 s[2:3], -1, 0
	v_cmp_gt_u32_e32 vcc, 64, v188
	s_and_b64 s[2:3], s[2:3], vcc
	s_and_saveexec_b64 s[6:7], s[2:3]
	s_cbranch_execz .LBB0_698
	s_lshl_b32 s8, s98, 6
	v_mov_b32_e32 v0, 0xff
	v_bitop3_b32 v0, s8, v0, v188 bitop3:0xc8
	v_lshlrev_b32_e32 v0, 2, v0
	v_mov_b32_e32 v1, 0
	s_and_b32 s4, s98, 4
	v_lshl_add_u64 v[2:3], s[86:87], 0, v[0:1]
	s_mov_b64 s[2:3], 0x2640000
	s_mov_b32 s5, 0
	v_lshl_add_u64 v[4:5], v[2:3], 0, s[2:3]
	s_lshl_b32 s4, s4, 15
	v_lshl_add_u64 v[2:3], v[4:5], 0, s[4:5]
	global_load_dword v22, v[2:3], off
	global_load_dword v23, v[2:3], off offset:1024
	global_load_dword v24, v[2:3], off offset:2048
	global_load_dword v25, v[2:3], off offset:3072
	s_movk_i32 s2, 0x1000
	v_add_co_u32_e32 v6, vcc, s2, v2
	s_movk_i32 s3, 0x2000
	s_nop 0
	v_addc_co_u32_e32 v7, vcc, 0, v3, vcc
	v_add_co_u32_e32 v8, vcc, s3, v2
	s_movk_i32 s4, 0x3000
	s_nop 0
	v_addc_co_u32_e32 v9, vcc, 0, v3, vcc
	v_add_co_u32_e32 v10, vcc, s4, v2
	s_movk_i32 s9, 0x4000
	s_nop 0
	v_addc_co_u32_e32 v11, vcc, 0, v3, vcc
	v_add_co_u32_e32 v12, vcc, s9, v2
	s_movk_i32 s10, 0x5000
	s_nop 0
	v_addc_co_u32_e32 v13, vcc, 0, v3, vcc
	v_add_co_u32_e32 v14, vcc, s10, v2
	s_movk_i32 s11, 0x6000
	s_nop 0
	v_addc_co_u32_e32 v15, vcc, 0, v3, vcc
	s_waitcnt vmcnt(0)
	v_add_co_u32_e32 v16, vcc, s11, v2
	s_movk_i32 s12, 0x7000
	s_nop 0
	v_addc_co_u32_e32 v17, vcc, 0, v3, vcc
	v_add_co_u32_e32 v18, vcc, s12, v2
	s_mov_b32 s13, 0x8000
	s_nop 0
	v_addc_co_u32_e32 v19, vcc, 0, v3, vcc
	global_load_dword v72, v[6:7], off offset:1024
	global_load_dword v73, v[6:7], off offset:2048
	global_load_dword v74, v[6:7], off offset:3072
	global_load_dword v75, v[10:11], off offset:1024
	global_load_dword v76, v[8:9], off offset:-4096
	global_load_dword v77, v[8:9], off
	global_load_dword v78, v[8:9], off offset:1024
	global_load_dword v79, v[8:9], off offset:2048
	global_load_dword v80, v[8:9], off offset:3072
	global_load_dword v81, v[12:13], off offset:-4096
	global_load_dword v82, v[12:13], off
	global_load_dword v83, v[12:13], off offset:1024
	global_load_dword v84, v[12:13], off offset:2048
	global_load_dword v85, v[12:13], off offset:3072
	global_load_dword v86, v[16:17], off offset:-4096
	global_load_dword v87, v[16:17], off
	global_load_dword v88, v[16:17], off offset:1024
	global_load_dword v89, v[16:17], off offset:2048
	global_load_dword v90, v[16:17], off offset:3072
	global_load_dword v91, v[10:11], off offset:2048
	global_load_dword v92, v[10:11], off offset:3072
	global_load_dword v93, v[14:15], off offset:1024
	global_load_dword v94, v[14:15], off offset:2048
	global_load_dword v95, v[14:15], off offset:3072
	global_load_dword v96, v[18:19], off offset:1024
	global_load_dword v97, v[18:19], off offset:2048
	global_load_dword v98, v[18:19], off offset:3072
	v_add_co_u32_e32 v20, vcc, s13, v2
	s_mov_b32 s14, 0x9000
	s_nop 0
	v_addc_co_u32_e32 v21, vcc, 0, v3, vcc
	v_add_co_u32_e32 v10, vcc, s14, v2
	s_mov_b32 s2, 0xa000
	s_nop 0
	v_addc_co_u32_e32 v11, vcc, 0, v3, vcc
	v_add_co_u32_e32 v12, vcc, s2, v2
	s_mov_b32 s2, 0xb000
	s_nop 0
	v_addc_co_u32_e32 v13, vcc, 0, v3, vcc
	global_load_dword v100, v[20:21], off offset:-4096
	global_load_dword v101, v[20:21], off
	global_load_dword v102, v[20:21], off offset:1024
	global_load_dword v103, v[20:21], off offset:2048
	global_load_dword v104, v[20:21], off offset:3072
	global_load_dword v105, v[12:13], off offset:-4096
	global_load_dword v106, v[12:13], off
	global_load_dword v107, v[12:13], off offset:1024
	v_or_b32_e32 v0, s8, v188
	v_lshl_add_u64 v[0:1], v[0:1], 2, s[86:87]
	v_add_f32_e32 v6, 0, v22
	v_add_f32_e32 v6, v6, v23
	v_add_f32_e32 v6, v6, v24
	v_add_f32_e32 v99, v6, v25
	v_add_co_u32_e32 v6, vcc, s2, v2
	s_mov_b32 s2, 0xc000
	s_nop 0
	v_addc_co_u32_e32 v7, vcc, 0, v3, vcc
	v_add_co_u32_e32 v8, vcc, s2, v2
	s_lshl_b32 s2, s98, 15
	s_nop 0
	v_addc_co_u32_e32 v9, vcc, 0, v3, vcc
	global_load_dword v108, v[12:13], off offset:2048
	global_load_dword v109, v[12:13], off offset:3072
	global_load_dword v110, v[8:9], off offset:-4096
	global_load_dword v111, v[10:11], off offset:1024
	global_load_dword v112, v[10:11], off offset:2048
	global_load_dword v113, v[10:11], off offset:3072
	global_load_dword v114, v[6:7], off offset:1024
	global_load_dword v115, v[6:7], off offset:2048
	s_or_b32 s4, s2, 0x18000
	v_lshl_add_u64 v[10:11], v[4:5], 0, s[4:5]
	s_or_b32 s4, s2, 0x18400
	v_lshl_add_u64 v[12:13], v[4:5], 0, s[4:5]
	s_or_b32 s4, s2, 0x18800
	v_lshl_add_u64 v[14:15], v[4:5], 0, s[4:5]
	s_or_b32 s4, s2, 0x18c00
	v_lshl_add_u64 v[16:17], v[4:5], 0, s[4:5]
	s_or_b32 s4, s2, 0x19000
	v_lshl_add_u64 v[24:25], v[4:5], 0, s[4:5]
	s_or_b32 s4, s2, 0x19400
	v_lshl_add_u64 v[28:29], v[4:5], 0, s[4:5]
	s_or_b32 s4, s2, 0x19800
	v_lshl_add_u64 v[30:31], v[4:5], 0, s[4:5]
	s_or_b32 s4, s2, 0x19c00
	v_lshl_add_u64 v[32:33], v[4:5], 0, s[4:5]
	s_or_b32 s4, s2, 0x1a000
	v_lshl_add_u64 v[34:35], v[4:5], 0, s[4:5]
	s_or_b32 s4, s2, 0x1a400
	v_lshl_add_u64 v[18:19], v[4:5], 0, s[4:5]
	s_or_b32 s4, s2, 0x1a800
	v_lshl_add_u64 v[20:21], v[4:5], 0, s[4:5]
	s_or_b32 s4, s2, 0x1ac00
	v_lshl_add_u64 v[22:23], v[4:5], 0, s[4:5]
	s_or_b32 s4, s2, 0x1b000
	v_lshl_add_u64 v[26:27], v[4:5], 0, s[4:5]
	s_or_b32 s4, s2, 0x1b400
	v_lshl_add_u64 v[36:37], v[4:5], 0, s[4:5]
	s_or_b32 s4, s2, 0x1b800
	v_lshl_add_u64 v[38:39], v[4:5], 0, s[4:5]
	s_or_b32 s4, s2, 0x1bc00
	v_lshl_add_u64 v[40:41], v[4:5], 0, s[4:5]
	s_or_b32 s4, s2, 0x1c000
	v_lshl_add_u64 v[42:43], v[4:5], 0, s[4:5]
	s_or_b32 s4, s2, 0x1c400
	v_lshl_add_u64 v[44:45], v[4:5], 0, s[4:5]
	s_or_b32 s4, s2, 0x1c800
	v_lshl_add_u64 v[46:47], v[4:5], 0, s[4:5]
	s_or_b32 s4, s2, 0x1cc00
	v_lshl_add_u64 v[48:49], v[4:5], 0, s[4:5]
	s_or_b32 s4, s2, 0x1d000
	v_lshl_add_u64 v[50:51], v[4:5], 0, s[4:5]
	s_or_b32 s4, s2, 0x1d400
	v_lshl_add_u64 v[52:53], v[4:5], 0, s[4:5]
	s_or_b32 s4, s2, 0x1d800
	v_lshl_add_u64 v[54:55], v[4:5], 0, s[4:5]
	s_or_b32 s4, s2, 0x1dc00
	v_lshl_add_u64 v[56:57], v[4:5], 0, s[4:5]
	s_or_b32 s4, s2, 0x1e000
	v_lshl_add_u64 v[58:59], v[4:5], 0, s[4:5]
	s_or_b32 s4, s2, 0x1e400
	v_lshl_add_u64 v[60:61], v[4:5], 0, s[4:5]
	s_or_b32 s4, s2, 0x1e800
	v_lshl_add_u64 v[62:63], v[4:5], 0, s[4:5]
	s_or_b32 s4, s2, 0x1ec00
	v_lshl_add_u64 v[64:65], v[4:5], 0, s[4:5]
	s_or_b32 s4, s2, 0x1f000
	v_lshl_add_u64 v[66:67], v[4:5], 0, s[4:5]
	s_or_b32 s4, s2, 0x1f400
	v_lshl_add_u64 v[68:69], v[4:5], 0, s[4:5]
	s_or_b32 s4, s2, 0x1f800
	v_lshl_add_u64 v[70:71], v[4:5], 0, s[4:5]
	s_or_b32 s4, s2, 0x1fc00
	v_lshl_add_u64 v[4:5], v[4:5], 0, s[4:5]
	global_load_dword v116, v[4:5], off
	s_waitcnt vmcnt(39)
	v_add_f32_e32 v4, v99, v76
	v_add_f32_e32 v4, v4, v72
	v_add_f32_e32 v4, v4, v73
	v_add_f32_e32 v4, v4, v74
	s_waitcnt vmcnt(38)
	v_add_f32_e32 v4, v4, v77
	s_waitcnt vmcnt(37)
	v_add_f32_e32 v4, v4, v78
	s_waitcnt vmcnt(36)
	v_add_f32_e32 v4, v4, v79
	s_waitcnt vmcnt(35)
	v_add_f32_e32 v4, v4, v80
	s_waitcnt vmcnt(34)
	v_add_f32_e32 v4, v4, v81
	v_add_f32_e32 v4, v4, v75
	s_waitcnt vmcnt(24)
	v_add_f32_e32 v4, v4, v91
	s_waitcnt vmcnt(23)
	v_add_f32_e32 v4, v4, v92
	v_add_f32_e32 v4, v4, v82
	v_add_f32_e32 v4, v4, v83
	v_add_f32_e32 v4, v4, v84
	v_add_f32_e32 v4, v4, v85
	v_add_f32_e32 v4, v4, v86
	s_waitcnt vmcnt(22)
	v_add_f32_e32 v4, v4, v93
	s_waitcnt vmcnt(21)
	v_add_f32_e32 v4, v4, v94
	s_waitcnt vmcnt(20)
	v_add_f32_e32 v4, v4, v95
	v_add_f32_e32 v4, v4, v87
	v_add_f32_e32 v4, v4, v88
	v_add_f32_e32 v4, v4, v89
	v_add_f32_e32 v4, v4, v90
	s_waitcnt vmcnt(16)
	v_add_f32_e32 v4, v4, v100
	v_add_f32_e32 v4, v4, v96
	v_add_f32_e32 v4, v4, v97
	s_mov_b32 s2, 0xd000
	v_add_f32_e32 v74, v4, v98
	v_add_co_u32_e32 v4, vcc, s2, v2
	s_mov_b32 s2, 0xe000
	s_nop 0
	v_addc_co_u32_e32 v5, vcc, 0, v3, vcc
	v_add_co_u32_e32 v72, vcc, s2, v2
	s_waitcnt vmcnt(15)
	v_add_f32_e32 v74, v74, v101
	v_addc_co_u32_e32 v73, vcc, 0, v3, vcc
	global_load_dword v80, v[8:9], off
	global_load_dword v81, v[8:9], off offset:1024
	global_load_dword v82, v[8:9], off offset:2048
	global_load_dword v83, v[8:9], off offset:3072
	global_load_dword v84, v[72:73], off offset:-4096
	global_load_dword v85, v[6:7], off offset:3072
	global_load_dword v86, v[4:5], off offset:1024
	global_load_dword v87, v[4:5], off offset:2048
	s_waitcnt vmcnt(22)
	v_add_f32_e32 v74, v74, v102
	s_waitcnt vmcnt(21)
	v_add_f32_e32 v74, v74, v103
	s_mov_b32 s2, 0xf000
	s_waitcnt vmcnt(20)
	v_add_f32_e32 v74, v74, v104
	v_add_co_u32_e32 v6, vcc, s2, v2
	s_waitcnt vmcnt(19)
	v_add_f32_e32 v74, v74, v105
	v_addc_co_u32_e32 v7, vcc, 0, v3, vcc
	s_mov_b32 s2, 0x10000
	s_waitcnt vmcnt(13)
	v_add_f32_e32 v74, v74, v111
	v_add_co_u32_e32 v8, vcc, s2, v2
	s_waitcnt vmcnt(12)
	v_add_f32_e32 v74, v74, v112
	v_addc_co_u32_e32 v9, vcc, 0, v3, vcc
	s_waitcnt vmcnt(11)
	v_add_f32_e32 v74, v74, v113
	global_load_dword v89, v[72:73], off
	global_load_dword v90, v[72:73], off offset:1024
	global_load_dword v91, v[72:73], off offset:2048
	global_load_dword v92, v[72:73], off offset:3072
	global_load_dword v93, v[8:9], off offset:-4096
	global_load_dword v94, v[8:9], off
	global_load_dword v95, v[8:9], off offset:1024
	global_load_dword v96, v[8:9], off offset:2048
	v_add_f32_e32 v74, v74, v106
	v_add_f32_e32 v74, v74, v107
	v_add_f32_e32 v74, v74, v108
	v_add_f32_e32 v74, v74, v109
	s_mov_b32 s2, 0x11000
	v_add_f32_e32 v74, v74, v110
	v_add_co_u32_e32 v72, vcc, s2, v2
	s_waitcnt vmcnt(18)
	v_add_f32_e32 v74, v74, v114
	v_addc_co_u32_e32 v73, vcc, 0, v3, vcc
	s_mov_b32 s2, 0x12000
	s_waitcnt vmcnt(17)
	v_add_f32_e32 v88, v74, v115
	v_add_co_u32_e32 v74, vcc, s2, v2
	s_mov_b32 s2, 0x13000
	s_nop 0
	v_addc_co_u32_e32 v75, vcc, 0, v3, vcc
	v_add_co_u32_e32 v76, vcc, s2, v2
	s_mov_b32 s2, 0x14000
	s_nop 0
	v_addc_co_u32_e32 v77, vcc, 0, v3, vcc
	v_add_co_u32_e32 v78, vcc, s2, v2
	s_mov_b32 s2, 0x15000
	s_nop 0
	v_addc_co_u32_e32 v79, vcc, 0, v3, vcc
	global_load_dword v97, v[4:5], off offset:3072
	global_load_dword v98, v[6:7], off offset:1024
	global_load_dword v99, v[6:7], off offset:2048
	global_load_dword v100, v[6:7], off offset:3072
	global_load_dword v101, v[72:73], off offset:1024
	global_load_dword v102, v[72:73], off offset:2048
	global_load_dword v103, v[72:73], off offset:3072
	global_load_dword v104, v[76:77], off offset:1024
	global_load_dword v105, v[8:9], off offset:3072
	global_load_dword v106, v[74:75], off offset:-4096
	global_load_dword v107, v[74:75], off
	global_load_dword v108, v[74:75], off offset:1024
	global_load_dword v109, v[74:75], off offset:2048
	global_load_dword v110, v[74:75], off offset:3072
	global_load_dword v111, v[78:79], off offset:-4096
	global_load_dword v8, v[78:79], off
	v_add_co_u32_e32 v4, vcc, s2, v2
	s_mov_b32 s2, 0x16000
	s_nop 0
	v_addc_co_u32_e32 v5, vcc, 0, v3, vcc
	v_add_co_u32_e32 v6, vcc, s2, v2
	s_mov_b32 s2, 0x17000
	s_nop 0
	v_addc_co_u32_e32 v7, vcc, 0, v3, vcc
	global_load_dword v9, v[76:77], off offset:2048
	global_load_dword v72, v[76:77], off offset:3072
	global_load_dword v73, v[4:5], off offset:1024
	global_load_dword v74, v[4:5], off offset:2048
	global_load_dword v75, v[4:5], off offset:3072
	global_load_dword v112, v[78:79], off offset:1024
	global_load_dword v113, v[78:79], off offset:2048
	global_load_dword v114, v[78:79], off offset:3072
	global_load_dword v115, v[6:7], off offset:-4096
	global_load_dword v117, v[6:7], off
	global_load_dword v118, v[6:7], off offset:1024
	global_load_dword v119, v[6:7], off offset:2048
	global_load_dword v120, v[6:7], off offset:3072
	v_add_co_u32_e32 v2, vcc, s2, v2
	s_nop 1
	v_addc_co_u32_e32 v3, vcc, 0, v3, vcc
	global_load_dword v4, v[2:3], off
	global_load_dword v5, v[2:3], off offset:1024
	global_load_dword v6, v[2:3], off offset:2048
	global_load_dword v7, v[2:3], off offset:3072
	global_load_dword v76, v[10:11], off
	global_load_dword v77, v[12:13], off
	global_load_dword v78, v[14:15], off
	global_load_dword v79, v[16:17], off
	global_load_dword v121, v[24:25], off
	global_load_dword v122, v[28:29], off
	global_load_dword v123, v[30:31], off
	global_load_dword v124, v[32:33], off
	global_load_dword v125, v[34:35], off
	global_load_dword v2, v[18:19], off
	global_load_dword v3, v[20:21], off
	global_load_dword v10, v[22:23], off
	global_load_dword v11, v[26:27], off
	global_load_dword v12, v[36:37], off
	global_load_dword v13, v[38:39], off
	global_load_dword v14, v[40:41], off
	global_load_dword v15, v[42:43], off
	global_load_dword v16, v[44:45], off
	global_load_dword v17, v[46:47], off
	global_load_dword v24, v[48:49], off
	global_load_dword v25, v[50:51], off
	global_load_dword v28, v[52:53], off
	global_load_dword v29, v[54:55], off
	global_load_dword v30, v[56:57], off
	global_load_dword v18, v[58:59], off
	global_load_dword v19, v[60:61], off
	global_load_dword v20, v[62:63], off
	global_load_dword v21, v[64:65], off
	global_load_dword v22, v[66:67], off
	global_load_dword v23, v[68:69], off
	global_load_dword v26, v[70:71], off
	v_add_co_u32_e32 v0, vcc, 0x2680000, v0
	s_waitcnt vmcnt(62)
	v_add_f32_e32 v27, v88, v85
	v_add_f32_e32 v27, v27, v80
	v_add_f32_e32 v27, v27, v81
	v_add_f32_e32 v27, v27, v82
	v_add_f32_e32 v27, v27, v83
	v_add_f32_e32 v27, v27, v84
	v_add_f32_e32 v27, v27, v86
	v_add_f32_e32 v27, v27, v87
	v_addc_co_u32_e32 v1, vcc, 0, v1, vcc
	v_add_f32_e32 v27, v27, v97
	v_add_f32_e32 v27, v27, v89
	v_add_f32_e32 v27, v27, v90
	v_add_f32_e32 v27, v27, v91
	v_add_f32_e32 v27, v27, v92
	v_add_f32_e32 v27, v27, v93
	v_add_f32_e32 v27, v27, v98
	s_waitcnt vmcnt(61)
	v_add_f32_e32 v27, v27, v99
	s_waitcnt vmcnt(60)
	v_add_f32_e32 v27, v27, v100
	v_add_f32_e32 v27, v27, v94
	v_add_f32_e32 v27, v27, v95
	v_add_f32_e32 v27, v27, v96
	s_waitcnt vmcnt(55)
	v_add_f32_e32 v27, v27, v105
	s_waitcnt vmcnt(54)
	v_add_f32_e32 v27, v27, v106
	v_add_f32_e32 v27, v27, v101
	v_add_f32_e32 v27, v27, v102
	v_add_f32_e32 v27, v27, v103
	s_waitcnt vmcnt(53)
	v_add_f32_e32 v27, v27, v107
	s_waitcnt vmcnt(52)
	v_add_f32_e32 v27, v27, v108
	s_waitcnt vmcnt(51)
	v_add_f32_e32 v27, v27, v109
	s_waitcnt vmcnt(50)
	v_add_f32_e32 v27, v27, v110
	s_waitcnt vmcnt(49)
	v_add_f32_e32 v27, v27, v111
	v_add_f32_e32 v27, v27, v104
	s_waitcnt vmcnt(47)
	v_add_f32_e32 v9, v27, v9
	s_waitcnt vmcnt(46)
	v_add_f32_e32 v9, v9, v72
	v_add_f32_e32 v8, v9, v8
	s_waitcnt vmcnt(42)
	v_add_f32_e32 v8, v8, v112
	s_waitcnt vmcnt(41)
	v_add_f32_e32 v8, v8, v113
	s_waitcnt vmcnt(40)
	v_add_f32_e32 v8, v8, v114
	s_waitcnt vmcnt(39)
	v_add_f32_e32 v8, v8, v115
	v_add_f32_e32 v8, v8, v73
	v_add_f32_e32 v8, v8, v74
	v_add_f32_e32 v8, v8, v75
	s_waitcnt vmcnt(38)
	v_add_f32_e32 v8, v8, v117
	s_waitcnt vmcnt(37)
	v_add_f32_e32 v8, v8, v118
	s_waitcnt vmcnt(36)
	v_add_f32_e32 v8, v8, v119
	s_waitcnt vmcnt(35)
	v_add_f32_e32 v8, v8, v120
	s_waitcnt vmcnt(34)
	v_add_f32_e32 v4, v8, v4
	s_waitcnt vmcnt(33)
	v_add_f32_e32 v4, v4, v5
	s_waitcnt vmcnt(32)
	v_add_f32_e32 v4, v4, v6
	s_waitcnt vmcnt(31)
	v_add_f32_e32 v4, v4, v7
	s_waitcnt vmcnt(30)
	v_add_f32_e32 v4, v4, v76
	s_waitcnt vmcnt(29)
	v_add_f32_e32 v4, v4, v77
	s_waitcnt vmcnt(28)
	v_add_f32_e32 v4, v4, v78
	s_waitcnt vmcnt(27)
	v_add_f32_e32 v4, v4, v79
	s_waitcnt vmcnt(26)
	v_add_f32_e32 v4, v4, v121
	s_waitcnt vmcnt(25)
	v_add_f32_e32 v4, v4, v122
	s_waitcnt vmcnt(24)
	v_add_f32_e32 v4, v4, v123
	s_waitcnt vmcnt(23)
	v_add_f32_e32 v4, v4, v124
	s_waitcnt vmcnt(22)
	v_add_f32_e32 v4, v4, v125
	s_waitcnt vmcnt(21)
	v_add_f32_e32 v2, v4, v2
	s_waitcnt vmcnt(20)
	v_add_f32_e32 v2, v2, v3
	s_waitcnt vmcnt(19)
	v_add_f32_e32 v2, v2, v10
	s_waitcnt vmcnt(18)
	v_add_f32_e32 v2, v2, v11
	s_waitcnt vmcnt(17)
	v_add_f32_e32 v2, v2, v12
	s_waitcnt vmcnt(16)
	v_add_f32_e32 v2, v2, v13
	s_waitcnt vmcnt(15)
	v_add_f32_e32 v2, v2, v14
	s_waitcnt vmcnt(14)
	v_add_f32_e32 v2, v2, v15
	s_waitcnt vmcnt(13)
	v_add_f32_e32 v2, v2, v16
	s_waitcnt vmcnt(12)
	v_add_f32_e32 v2, v2, v17
	s_waitcnt vmcnt(11)
	v_add_f32_e32 v2, v2, v24
	s_waitcnt vmcnt(10)
	v_add_f32_e32 v2, v2, v25
	s_waitcnt vmcnt(9)
	v_add_f32_e32 v2, v2, v28
	s_waitcnt vmcnt(8)
	v_add_f32_e32 v2, v2, v29
	s_waitcnt vmcnt(7)
	v_add_f32_e32 v2, v2, v30
	s_waitcnt vmcnt(6)
	v_add_f32_e32 v2, v2, v18
	s_waitcnt vmcnt(5)
	v_add_f32_e32 v2, v2, v19
	s_waitcnt vmcnt(4)
	v_add_f32_e32 v2, v2, v20
	s_waitcnt vmcnt(3)
	v_add_f32_e32 v2, v2, v21
	s_waitcnt vmcnt(2)
	v_add_f32_e32 v2, v2, v22
	s_waitcnt vmcnt(1)
	v_add_f32_e32 v2, v2, v23
	s_waitcnt vmcnt(0)
	v_add_f32_e32 v2, v2, v26
	v_add_f32_e32 v2, v2, v116
	global_store_dword v[0:1], v2, off
